# v59 + nt hint on the 16 final-output (out, f32) stores of P14
# baseline (speedup 1.0000x reference)
.LBB0_2791:
	s_mov_b32 s40, 25
	s_ashr_i32 s41, s40, 31
	s_lshl_b64 s[40:41], s[40:41], 3
	s_add_u32 s40, s68, s40
	s_addc_u32 s41, s69, s41
	v_mov_b32_e32 v2, v0
	s_add_u32 s42, s70, s0
	s_load_dwordx2 s[40:41], s[40:41], 0x0
	s_addc_u32 s43, s71, s1
	v_and_b32_e32 v4, 63, v2
	v_lshlrev_b32_e32 v3, 16, v2
	v_and_b32_e32 v2, 15, v2
	s_add_u32 s44, s70, s2
	v_lshlrev_b32_e32 v5, 2, v4
	v_lshlrev_b32_e32 v18, 3, v4
	v_lshlrev_b32_e32 v2, 3, v2
	s_addc_u32 s45, s71, s3
	global_load_dword v45, v5, s[42:43]
	v_and_or_b32 v26, v3, s16, v2
	v_lshl_add_u64 v[2:3], s[44:45], 0, v[18:19]
	v_add_co_u32_e32 v24, vcc, s18, v2
	v_lshlrev_b32_e32 v18, 4, v4
	s_nop 0
	v_addc_co_u32_e32 v25, vcc, 0, v3, vcc
	v_add_co_u32_e32 v22, vcc, s28, v2
	s_waitcnt lgkmcnt(0)
	v_lshl_add_u64 v[34:35], s[40:41], 0, v[18:19]
	v_addc_co_u32_e32 v23, vcc, 0, v3, vcc
	global_load_dwordx4 v[2:5], v18, s[40:41]
	global_load_dwordx4 v[6:9], v18, s[40:41] offset:1024
	global_load_dwordx4 v[10:13], v18, s[40:41] offset:2048
	global_load_dwordx4 v[14:17], v18, s[40:41] offset:3072
	global_load_dwordx2 v[30:31], v[22:23], off offset:-4096
	s_add_u32 s42, s70, s12
	v_add_co_u32_e32 v36, vcc, s23, v34
	v_mov_b32_e32 v27, v19
	s_addc_u32 s43, s71, s13
	v_addc_co_u32_e32 v37, vcc, 0, v35, vcc
	v_lshl_add_u64 v[32:33], s[42:43], 0, v[26:27]
	v_add_co_u32_e32 v26, vcc, s29, v34
	v_lshl_add_u64 v[20:21], s[6:7], 0, v[18:19]
	s_nop 0
	v_addc_co_u32_e32 v27, vcc, 0, v35, vcc
	v_add_co_u32_e32 v38, vcc, s23, v20
	s_add_i32 s72, s72, s74
	s_nop 0
	v_addc_co_u32_e32 v39, vcc, 0, v21, vcc
	v_add_co_u32_e32 v28, vcc, s29, v20
	s_add_u32 s2, s2, s4
	s_nop 0
	v_addc_co_u32_e32 v29, vcc, 0, v21, vcc
	v_add_co_u32_e32 v34, vcc, s35, v34
	s_addc_u32 s3, s3, s5
	s_nop 0
	v_addc_co_u32_e32 v35, vcc, 0, v35, vcc
	v_add_co_u32_e32 v46, vcc, s17, v32
	s_nop 1
	v_addc_co_u32_e32 v47, vcc, 0, v33, vcc
	v_add_co_u32_e32 v48, vcc, s19, v32
	s_nop 1
	v_addc_co_u32_e32 v49, vcc, 0, v33, vcc
	v_add_co_u32_e32 v50, vcc, s20, v32
	s_nop 1
	v_addc_co_u32_e32 v51, vcc, 0, v33, vcc
	v_add_co_u32_e32 v52, vcc, s21, v32
	s_nop 1
	v_addc_co_u32_e32 v53, vcc, 0, v33, vcc
	global_load_dwordx2 v[72:73], v[46:47], off
	global_load_dwordx2 v[74:75], v[24:25], off offset:512
	global_load_dwordx2 v[76:77], v[48:49], off
	global_load_dwordx2 v[78:79], v[24:25], off offset:1024
	global_load_dwordx2 v[80:81], v[50:51], off
	global_load_dwordx2 v[82:83], v[52:53], off
	global_load_dwordx2 v[84:85], v[24:25], off offset:1536
	v_add_co_u32_e32 v54, vcc, s22, v32
	s_waitcnt vmcnt(12)
	ds_bpermute_b32 v50, v1, v45
	v_addc_co_u32_e32 v55, vcc, 0, v33, vcc
	v_add_co_u32_e32 v56, vcc, s24, v32
	s_waitcnt vmcnt(7)
	v_lshlrev_b32_e32 v46, 16, v30
	v_and_b32_e32 v47, 0xffff0000, v30
	s_waitcnt lgkmcnt(0)
	v_add_f32_e32 v30, v45, v50
	v_lshlrev_b32_e32 v48, 16, v31
	v_and_b32_e32 v49, 0xffff0000, v31
	ds_bpermute_b32 v31, v201, v30
	v_addc_co_u32_e32 v57, vcc, 0, v33, vcc
	v_add_co_u32_e32 v58, vcc, s25, v32
	s_waitcnt lgkmcnt(0)
	v_add_f32_e32 v30, v30, v31
	ds_bpermute_b32 v31, v205, v30
	v_addc_co_u32_e32 v59, vcc, 0, v33, vcc
	v_add_co_u32_e32 v60, vcc, s26, v32
	s_waitcnt lgkmcnt(0)
	v_add_f32_e32 v30, v30, v31
	ds_bpermute_b32 v31, v211, v30
	v_addc_co_u32_e32 v61, vcc, 0, v33, vcc
	v_add_co_u32_e32 v62, vcc, s27, v32
	s_waitcnt lgkmcnt(0)
	v_add_f32_e32 v30, v30, v31
	ds_bpermute_b32 v31, v218, v30
	v_addc_co_u32_e32 v63, vcc, 0, v33, vcc
	v_add_co_u32_e32 v64, vcc, s30, v32
	s_waitcnt lgkmcnt(0)
	v_add_f32_e32 v30, v30, v31
	ds_bpermute_b32 v31, v219, v30
	v_addc_co_u32_e32 v65, vcc, 0, v33, vcc
	v_add_co_u32_e32 v66, vcc, s31, v32
	s_waitcnt lgkmcnt(0)
	v_add_f32_e32 v30, v30, v31
	v_fmamk_f32 v30, v30, 0x39800000, v44
	v_rsq_f32_e32 v30, v30
	v_addc_co_u32_e32 v67, vcc, 0, v33, vcc
	v_add_co_u32_e32 v68, vcc, s33, v32
	v_mul_f32_e32 v30, 0.5, v30
	v_pk_mul_f32 v[46:47], v[30:31], v[46:47] op_sel_hi:[0,1]
	s_waitcnt vmcnt(6)
	v_lshlrev_b32_e32 v50, 16, v72
	v_and_b32_e32 v51, 0xffff0000, v72
	v_lshlrev_b32_e32 v52, 16, v73
	v_and_b32_e32 v53, 0xffff0000, v73
	s_waitcnt vmcnt(5)
	v_lshlrev_b32_e32 v72, 16, v74
	v_and_b32_e32 v73, 0xffff0000, v74
	v_lshlrev_b32_e32 v74, 16, v75
	v_and_b32_e32 v75, 0xffff0000, v75
	s_waitcnt vmcnt(3)
	v_lshlrev_b32_e32 v88, 16, v78
	v_and_b32_e32 v89, 0xffff0000, v78
	v_lshlrev_b32_e32 v78, 16, v79
	v_and_b32_e32 v79, 0xffff0000, v79
	s_waitcnt vmcnt(0)
	v_lshlrev_b32_e32 v92, 16, v84
	v_and_b32_e32 v93, 0xffff0000, v84
	v_lshlrev_b32_e32 v84, 16, v85
	v_and_b32_e32 v85, 0xffff0000, v85
	v_pk_mul_f32 v[48:49], v[30:31], v[48:49] op_sel_hi:[0,1]
	v_lshlrev_b32_e32 v86, 16, v76
	v_and_b32_e32 v87, 0xffff0000, v76
	v_lshlrev_b32_e32 v76, 16, v77
	v_and_b32_e32 v77, 0xffff0000, v77
	v_lshlrev_b32_e32 v90, 16, v80
	v_and_b32_e32 v91, 0xffff0000, v80
	v_lshlrev_b32_e32 v80, 16, v81
	v_and_b32_e32 v81, 0xffff0000, v81
	v_lshlrev_b32_e32 v94, 16, v82
	v_and_b32_e32 v95, 0xffff0000, v82
	v_lshlrev_b32_e32 v82, 16, v83
	v_and_b32_e32 v83, 0xffff0000, v83
	v_pk_mul_f32 v[72:73], v[30:31], v[72:73] op_sel_hi:[0,1]
	v_pk_mul_f32 v[74:75], v[30:31], v[74:75] op_sel_hi:[0,1]
	v_pk_mul_f32 v[88:89], v[30:31], v[88:89] op_sel_hi:[0,1]
	v_pk_mul_f32 v[78:79], v[30:31], v[78:79] op_sel_hi:[0,1]
	v_pk_mul_f32 v[92:93], v[30:31], v[92:93] op_sel_hi:[0,1]
	v_pk_mul_f32 v[84:85], v[30:31], v[84:85] op_sel_hi:[0,1]
	v_pk_fma_f32 v[4:5], v[4:5], v[48:49], v[52:53]
	v_pk_fma_f32 v[2:3], v[2:3], v[46:47], v[50:51]
	v_pk_fma_f32 v[8:9], v[8:9], v[74:75], v[76:77]
	v_pk_fma_f32 v[6:7], v[6:7], v[72:73], v[86:87]
	v_pk_fma_f32 v[12:13], v[12:13], v[78:79], v[80:81]
	v_pk_fma_f32 v[10:11], v[10:11], v[88:89], v[90:91]
	v_pk_fma_f32 v[16:17], v[16:17], v[84:85], v[82:83]
	v_pk_fma_f32 v[14:15], v[14:15], v[92:93], v[94:95]
	global_store_dwordx4 v18, v[2:5], s[6:7] nt
	global_store_dwordx4 v18, v[6:9], s[6:7] offset:1024 nt
	global_store_dwordx4 v18, v[10:13], s[6:7] offset:2048 nt
	global_store_dwordx4 v18, v[14:17], s[6:7] offset:3072 nt
	global_load_dwordx2 v[46:47], v[24:25], off offset:2048
	global_load_dwordx2 v[48:49], v[54:55], off
	global_load_dwordx2 v[50:51], v[24:25], off offset:2560
	global_load_dwordx2 v[52:53], v[56:57], off
	global_load_dwordx2 v[72:73], v[24:25], off offset:3072
	global_load_dwordx2 v[74:75], v[58:59], off
	global_load_dwordx2 v[76:77], v[24:25], off offset:3584
	global_load_dwordx2 v[78:79], v[60:61], off
	global_load_dwordx4 v[2:5], v[26:27], off offset:-4096
	global_load_dwordx4 v[6:9], v[36:37], off offset:1024
	global_load_dwordx4 v[10:13], v[36:37], off offset:2048
	global_load_dwordx4 v[14:17], v[36:37], off offset:3072
	v_addc_co_u32_e32 v69, vcc, 0, v33, vcc
	v_add_co_u32_e32 v40, vcc, s34, v32
	s_add_u32 s6, s6, s8
	s_nop 0
	v_addc_co_u32_e32 v41, vcc, 0, v33, vcc
	v_add_co_u32_e32 v42, vcc, s36, v32
	s_addc_u32 s7, s7, s9
	s_nop 0
	v_addc_co_u32_e32 v43, vcc, 0, v33, vcc
	v_add_co_u32_e32 v70, vcc, s37, v32
	s_add_u32 s0, s0, s10
	s_nop 0
	v_addc_co_u32_e32 v71, vcc, 0, v33, vcc
	v_add_co_u32_e32 v32, vcc, s38, v32
	s_addc_u32 s1, s1, s11
	s_nop 0
	v_addc_co_u32_e32 v33, vcc, 0, v33, vcc
	v_add_co_u32_e32 v20, vcc, s35, v20
	s_add_u32 s12, s12, s14
	s_nop 0
	v_addc_co_u32_e32 v21, vcc, 0, v21, vcc
	s_addc_u32 s13, s13, s15
	s_cmpk_gt_i32 s72, 0x1fff
	s_waitcnt vmcnt(11)
	v_lshlrev_b32_e32 v24, 16, v46
	v_and_b32_e32 v25, 0xffff0000, v46
	v_lshlrev_b32_e32 v36, 16, v47
	v_and_b32_e32 v37, 0xffff0000, v47
	s_waitcnt vmcnt(10)
	v_lshlrev_b32_e32 v46, 16, v48
	v_and_b32_e32 v47, 0xffff0000, v48
	v_lshlrev_b32_e32 v48, 16, v49
	v_and_b32_e32 v49, 0xffff0000, v49
	s_waitcnt vmcnt(9)
	v_lshlrev_b32_e32 v54, 16, v50
	v_and_b32_e32 v55, 0xffff0000, v50
	v_lshlrev_b32_e32 v50, 16, v51
	v_and_b32_e32 v51, 0xffff0000, v51
	s_waitcnt vmcnt(7)
	v_lshlrev_b32_e32 v58, 16, v72
	v_and_b32_e32 v59, 0xffff0000, v72
	v_lshlrev_b32_e32 v60, 16, v73
	v_and_b32_e32 v61, 0xffff0000, v73
	s_waitcnt vmcnt(5)
	v_lshlrev_b32_e32 v80, 16, v76
	v_and_b32_e32 v81, 0xffff0000, v76
	v_lshlrev_b32_e32 v76, 16, v77
	v_and_b32_e32 v77, 0xffff0000, v77
	v_pk_mul_f32 v[24:25], v[30:31], v[24:25] op_sel_hi:[0,1]
	v_pk_mul_f32 v[36:37], v[30:31], v[36:37] op_sel_hi:[0,1]
	v_lshlrev_b32_e32 v56, 16, v52
	v_and_b32_e32 v57, 0xffff0000, v52
	v_lshlrev_b32_e32 v52, 16, v53
	v_and_b32_e32 v53, 0xffff0000, v53
	v_lshlrev_b32_e32 v72, 16, v74
	v_and_b32_e32 v73, 0xffff0000, v74
	v_lshlrev_b32_e32 v74, 16, v75
	v_and_b32_e32 v75, 0xffff0000, v75
	s_waitcnt vmcnt(4)
	v_lshlrev_b32_e32 v82, 16, v78
	v_and_b32_e32 v83, 0xffff0000, v78
	v_lshlrev_b32_e32 v78, 16, v79
	v_and_b32_e32 v79, 0xffff0000, v79
	v_pk_mul_f32 v[54:55], v[30:31], v[54:55] op_sel_hi:[0,1]
	v_pk_mul_f32 v[50:51], v[30:31], v[50:51] op_sel_hi:[0,1]
	v_pk_mul_f32 v[58:59], v[30:31], v[58:59] op_sel_hi:[0,1]
	v_pk_mul_f32 v[60:61], v[30:31], v[60:61] op_sel_hi:[0,1]
	v_pk_mul_f32 v[80:81], v[30:31], v[80:81] op_sel_hi:[0,1]
	v_pk_mul_f32 v[76:77], v[30:31], v[76:77] op_sel_hi:[0,1]
	s_waitcnt vmcnt(3)
	v_pk_fma_f32 v[4:5], v[4:5], v[36:37], v[48:49]
	v_pk_fma_f32 v[2:3], v[2:3], v[24:25], v[46:47]
	s_waitcnt vmcnt(2)
	v_pk_fma_f32 v[8:9], v[8:9], v[50:51], v[52:53]
	v_pk_fma_f32 v[6:7], v[6:7], v[54:55], v[56:57]
	s_waitcnt vmcnt(1)
	v_pk_fma_f32 v[12:13], v[12:13], v[60:61], v[74:75]
	v_pk_fma_f32 v[10:11], v[10:11], v[58:59], v[72:73]
	s_waitcnt vmcnt(0)
	v_pk_fma_f32 v[16:17], v[16:17], v[76:77], v[78:79]
	v_pk_fma_f32 v[14:15], v[14:15], v[80:81], v[82:83]
	global_store_dwordx4 v[28:29], v[2:5], off offset:-4096 nt
	global_store_dwordx4 v[38:39], v[6:9], off offset:1024 nt
	global_store_dwordx4 v[38:39], v[10:13], off offset:2048 nt
	global_store_dwordx4 v[38:39], v[14:17], off offset:3072 nt
	global_load_dwordx2 v[24:25], v[22:23], off
	global_load_dwordx2 v[36:37], v[62:63], off
	global_load_dwordx2 v[38:39], v[22:23], off offset:512
	global_load_dwordx2 v[46:47], v[64:65], off
	global_load_dwordx2 v[48:49], v[22:23], off offset:1024
	global_load_dwordx2 v[50:51], v[66:67], off
	global_load_dwordx2 v[52:53], v[22:23], off offset:1536
	global_load_dwordx2 v[54:55], v[68:69], off
	global_load_dwordx4 v[2:5], v[26:27], off
	global_load_dwordx4 v[6:9], v[26:27], off offset:1024
	global_load_dwordx4 v[10:13], v[26:27], off offset:2048
	global_load_dwordx4 v[14:17], v[26:27], off offset:3072
	s_waitcnt vmcnt(11)
	v_lshlrev_b32_e32 v26, 16, v24
	v_and_b32_e32 v27, 0xffff0000, v24
	v_lshlrev_b32_e32 v24, 16, v25
	v_and_b32_e32 v25, 0xffff0000, v25
	s_waitcnt vmcnt(10)
	v_lshlrev_b32_e32 v56, 16, v36
	v_and_b32_e32 v57, 0xffff0000, v36
	v_lshlrev_b32_e32 v36, 16, v37
	v_and_b32_e32 v37, 0xffff0000, v37
	s_waitcnt vmcnt(9)
	v_lshlrev_b32_e32 v58, 16, v38
	v_and_b32_e32 v59, 0xffff0000, v38
	v_lshlrev_b32_e32 v38, 16, v39
	v_and_b32_e32 v39, 0xffff0000, v39
	s_waitcnt vmcnt(7)
	v_lshlrev_b32_e32 v62, 16, v48
	v_and_b32_e32 v63, 0xffff0000, v48
	v_lshlrev_b32_e32 v48, 16, v49
	v_and_b32_e32 v49, 0xffff0000, v49
	s_waitcnt vmcnt(5)
	v_lshlrev_b32_e32 v66, 16, v52
	v_and_b32_e32 v67, 0xffff0000, v52
	v_lshlrev_b32_e32 v52, 16, v53
	v_and_b32_e32 v53, 0xffff0000, v53
	v_pk_mul_f32 v[26:27], v[30:31], v[26:27] op_sel_hi:[0,1]
	v_pk_mul_f32 v[24:25], v[30:31], v[24:25] op_sel_hi:[0,1]
	v_lshlrev_b32_e32 v60, 16, v46
	v_and_b32_e32 v61, 0xffff0000, v46
	v_lshlrev_b32_e32 v46, 16, v47
	v_and_b32_e32 v47, 0xffff0000, v47
	v_lshlrev_b32_e32 v64, 16, v50
	v_and_b32_e32 v65, 0xffff0000, v50
	v_lshlrev_b32_e32 v50, 16, v51
	v_and_b32_e32 v51, 0xffff0000, v51
	s_waitcnt vmcnt(4)
	v_lshlrev_b32_e32 v68, 16, v54
	v_and_b32_e32 v69, 0xffff0000, v54
	v_lshlrev_b32_e32 v54, 16, v55
	v_and_b32_e32 v55, 0xffff0000, v55
	v_pk_mul_f32 v[58:59], v[30:31], v[58:59] op_sel_hi:[0,1]
	v_pk_mul_f32 v[38:39], v[30:31], v[38:39] op_sel_hi:[0,1]
	v_pk_mul_f32 v[62:63], v[30:31], v[62:63] op_sel_hi:[0,1]
	v_pk_mul_f32 v[48:49], v[30:31], v[48:49] op_sel_hi:[0,1]
	v_pk_mul_f32 v[66:67], v[30:31], v[66:67] op_sel_hi:[0,1]
	v_pk_mul_f32 v[52:53], v[30:31], v[52:53] op_sel_hi:[0,1]
	s_waitcnt vmcnt(3)
	v_pk_fma_f32 v[4:5], v[4:5], v[24:25], v[36:37]
	v_pk_fma_f32 v[2:3], v[2:3], v[26:27], v[56:57]
	s_waitcnt vmcnt(2)
	v_pk_fma_f32 v[8:9], v[8:9], v[38:39], v[46:47]
	v_pk_fma_f32 v[6:7], v[6:7], v[58:59], v[60:61]
	s_waitcnt vmcnt(1)
	v_pk_fma_f32 v[12:13], v[12:13], v[48:49], v[50:51]
	v_pk_fma_f32 v[10:11], v[10:11], v[62:63], v[64:65]
	s_waitcnt vmcnt(0)
	v_pk_fma_f32 v[16:17], v[16:17], v[52:53], v[54:55]
	v_pk_fma_f32 v[14:15], v[14:15], v[66:67], v[68:69]
	global_store_dwordx4 v[28:29], v[2:5], off nt
	global_store_dwordx4 v[28:29], v[6:9], off offset:1024 nt
	global_store_dwordx4 v[28:29], v[10:13], off offset:2048 nt
	global_store_dwordx4 v[28:29], v[14:17], off offset:3072 nt
	global_load_dwordx2 v[24:25], v[22:23], off offset:2048
	global_load_dwordx2 v[26:27], v[40:41], off
	global_load_dwordx2 v[28:29], v[22:23], off offset:2560
	global_load_dwordx2 v[36:37], v[42:43], off
	global_load_dwordx2 v[38:39], v[22:23], off offset:3072
	global_load_dwordx2 v[46:47], v[70:71], off
	global_load_dwordx2 v[48:49], v[22:23], off offset:3584
	global_load_dwordx2 v[50:51], v[32:33], off
	global_load_dwordx4 v[2:5], v[34:35], off
	global_load_dwordx4 v[6:9], v[34:35], off offset:1024
	global_load_dwordx4 v[10:13], v[34:35], off offset:2048
	global_load_dwordx4 v[14:17], v[34:35], off offset:3072
	s_waitcnt vmcnt(11)
	v_lshlrev_b32_e32 v22, 16, v24
	v_and_b32_e32 v23, 0xffff0000, v24
	v_lshlrev_b32_e32 v24, 16, v25
	v_and_b32_e32 v25, 0xffff0000, v25
	s_waitcnt vmcnt(10)
	v_lshlrev_b32_e32 v32, 16, v26
	v_and_b32_e32 v33, 0xffff0000, v26
	v_lshlrev_b32_e32 v26, 16, v27
	v_and_b32_e32 v27, 0xffff0000, v27
	s_waitcnt vmcnt(9)
	v_lshlrev_b32_e32 v34, 16, v28
	v_and_b32_e32 v35, 0xffff0000, v28
	v_lshlrev_b32_e32 v28, 16, v29
	v_and_b32_e32 v29, 0xffff0000, v29
	s_waitcnt vmcnt(7)
	v_lshlrev_b32_e32 v42, 16, v38
	v_and_b32_e32 v43, 0xffff0000, v38
	v_lshlrev_b32_e32 v38, 16, v39
	v_and_b32_e32 v39, 0xffff0000, v39
	s_waitcnt vmcnt(5)
	v_lshlrev_b32_e32 v54, 16, v48
	v_and_b32_e32 v55, 0xffff0000, v48
	v_lshlrev_b32_e32 v48, 16, v49
	v_and_b32_e32 v49, 0xffff0000, v49
	v_pk_mul_f32 v[22:23], v[30:31], v[22:23] op_sel_hi:[0,1]
	v_pk_mul_f32 v[24:25], v[30:31], v[24:25] op_sel_hi:[0,1]
	v_lshlrev_b32_e32 v40, 16, v36
	v_and_b32_e32 v41, 0xffff0000, v36
	v_lshlrev_b32_e32 v36, 16, v37
	v_and_b32_e32 v37, 0xffff0000, v37
	v_lshlrev_b32_e32 v52, 16, v46
	v_and_b32_e32 v53, 0xffff0000, v46
	v_lshlrev_b32_e32 v46, 16, v47
	v_and_b32_e32 v47, 0xffff0000, v47
	s_waitcnt vmcnt(4)
	v_lshlrev_b32_e32 v56, 16, v50
	v_and_b32_e32 v57, 0xffff0000, v50
	v_lshlrev_b32_e32 v50, 16, v51
	v_and_b32_e32 v51, 0xffff0000, v51
	v_pk_mul_f32 v[34:35], v[30:31], v[34:35] op_sel_hi:[0,1]
	v_pk_mul_f32 v[28:29], v[30:31], v[28:29] op_sel_hi:[0,1]
	v_pk_mul_f32 v[42:43], v[30:31], v[42:43] op_sel_hi:[0,1]
	v_pk_mul_f32 v[38:39], v[30:31], v[38:39] op_sel_hi:[0,1]
	v_pk_mul_f32 v[54:55], v[30:31], v[54:55] op_sel_hi:[0,1]
	v_pk_mul_f32 v[30:31], v[30:31], v[48:49] op_sel_hi:[0,1]
	s_waitcnt vmcnt(3)
	v_pk_fma_f32 v[4:5], v[4:5], v[24:25], v[26:27]
	v_pk_fma_f32 v[2:3], v[2:3], v[22:23], v[32:33]
	s_waitcnt vmcnt(2)
	v_pk_fma_f32 v[8:9], v[8:9], v[28:29], v[36:37]
	v_pk_fma_f32 v[6:7], v[6:7], v[34:35], v[40:41]
	s_waitcnt vmcnt(1)
	v_pk_fma_f32 v[12:13], v[12:13], v[38:39], v[46:47]
	v_pk_fma_f32 v[10:11], v[10:11], v[42:43], v[52:53]
	s_waitcnt vmcnt(0)
	v_pk_fma_f32 v[16:17], v[16:17], v[30:31], v[50:51]
	v_pk_fma_f32 v[14:15], v[14:15], v[54:55], v[56:57]
	global_store_dwordx4 v[20:21], v[2:5], off nt
	global_store_dwordx4 v[20:21], v[6:9], off offset:1024 nt
	global_store_dwordx4 v[20:21], v[10:13], off offset:2048 nt
	global_store_dwordx4 v[20:21], v[14:17], off offset:3072 nt
	s_cbranch_scc0 .LBB0_2791
